# in-proj panel order: gelu panel 0 moved from the c_fl class to the class with the most slack
# speedup vs baseline: 1.0132x; 1.0132x over previous
.LBB0_249:
	v_writelane_b32 v253, s80, 2
	s_nop 1
	v_writelane_b32 v253, s81, 3
	v_writelane_b32 v253, s76, 4
	s_nop 1
	v_writelane_b32 v253, s77, 5
	s_or_b64 exec, exec, s[4:5]
	s_cmpk_lt_i32 s90, 0x400
	s_cselect_b64 s[4:5], -1, 0
	v_writelane_b32 v253, s4, 6
	s_ashr_i32 s66, s90, 31
	s_ashr_i32 s92, s60, 31
	v_writelane_b32 v253, s5, 7
	s_lshr_b32 s4, s66, 29
	s_add_i32 s4, s90, s4
	s_ashr_i32 s9, s4, 3
	s_and_b32 s4, s4, -8
	s_sub_i32 s10, s90, s4
	s_lshl_b32 s11, s10, 7
	s_cmp_eq_u32 s3, 15
	s_cselect_b64 s[4:5], -1, 0
	v_writelane_b32 v253, s4, 8
	s_cmp_eq_u32 s3, 14
	s_mul_i32 s8, s61, s60
	v_writelane_b32 v253, s5, 9
	s_cselect_b64 s[4:5], -1, 0
	v_writelane_b32 v253, s4, 10
	s_cmp_eq_u32 s3, 13
	s_mul_i32 s12, s10, 0x81
	v_writelane_b32 v253, s5, 11
	s_cselect_b64 s[4:5], -1, 0
	v_writelane_b32 v253, s4, 12
	s_cmp_eq_u32 s3, 12
	s_mul_i32 s96, s8, s2
	v_writelane_b32 v253, s5, 13
	s_cselect_b64 s[4:5], -1, 0
	v_writelane_b32 v253, s4, 14
	s_cmp_eq_u32 s3, 11
	v_lshlrev_b64 v[0:1], 2, v[0:1]
	v_writelane_b32 v253, s5, 15
	s_cselect_b64 s[4:5], -1, 0
	v_writelane_b32 v253, s4, 16
	s_cmp_eq_u32 s3, 10
	v_mov_b32_e32 v191, 0
	v_writelane_b32 v253, s5, 17
	s_cselect_b64 s[4:5], -1, 0
	v_writelane_b32 v253, s4, 18
	s_cmp_eq_u32 s3, 9
	s_mov_b32 s81, 0
	v_writelane_b32 v253, s5, 19
	s_cselect_b64 s[4:5], -1, 0
	v_writelane_b32 v253, s4, 20
	s_cmp_eq_u32 s3, 8
	s_movk_i32 s33, 0x200
	v_writelane_b32 v253, s5, 21
	s_cselect_b64 s[4:5], -1, 0
	v_writelane_b32 v253, s4, 22
	s_cmp_eq_u32 s3, 7
	s_movk_i32 s65, 0x2000
	v_writelane_b32 v253, s5, 23
	s_cselect_b64 s[4:5], -1, 0
	v_writelane_b32 v253, s4, 24
	s_cmp_eq_u32 s3, 6
	s_movk_i32 s82, 0x6000
	v_writelane_b32 v253, s5, 25
	s_cselect_b64 s[4:5], -1, 0
	v_writelane_b32 v253, s4, 26
	s_cmp_eq_u32 s3, 5
	v_mov_b32_e32 v192, 0x358637bd
	v_writelane_b32 v253, s5, 27
	s_cselect_b64 s[4:5], -1, 0
	v_writelane_b32 v253, s4, 28
	s_cmp_eq_u32 s3, 4
	v_mov_b32_e32 v185, 0x3ecc95a3
	v_writelane_b32 v253, s5, 29
	s_cselect_b64 s[4:5], -1, 0
	v_writelane_b32 v253, s4, 30
	s_cmp_eq_u32 s3, 3
	v_mov_b32_e32 v193, 1
	v_writelane_b32 v253, s5, 31
	s_cselect_b64 s[4:5], -1, 0
	v_writelane_b32 v253, s4, 32
	s_cmp_eq_u32 s3, 2
	v_mov_b64_e32 v[194:195], 0x400
	v_writelane_b32 v253, s5, 33
	s_cselect_b64 s[4:5], -1, 0
	v_writelane_b32 v253, s4, 34
	s_cmp_eq_u32 s3, 1
	v_mov_b64_e32 v[196:197], 0x3ff
	v_writelane_b32 v253, s5, 35
	s_cselect_b64 s[4:5], -1, 0
	v_writelane_b32 v253, s4, 36
	s_cmp_eq_u32 s3, 0
	v_mov_b32_e32 v224, 0x3e38aa3b
	v_writelane_b32 v253, s5, 37
	s_cselect_b64 s[4:5], -1, 0
	v_writelane_b32 v253, s4, 38
	s_cmpk_lt_i32 s78, 0x200
	v_mov_b32_e32 v225, 0x41b17218
	v_writelane_b32 v253, s5, 39
	s_cselect_b64 s[4:5], -1, 0
	s_lshl_b32 s72, s60, 1
	v_writelane_b32 v253, s4, 40
	s_cmpk_lt_i32 s78, 0x100
	v_mov_b32_e32 v226, 0x7f800000
	v_writelane_b32 v253, s5, 41
	s_cselect_b64 s[4:5], -1, 0
	v_writelane_b32 v253, s4, 42
	s_cmp_lt_i32 s78, 32
	v_mbcnt_hi_u32_b32 v227, -1, v78
	v_writelane_b32 v253, s5, 43
	s_cselect_b64 s[4:5], -1, 0
	v_writelane_b32 v253, s4, 44
	s_cmpk_eq_i32 s60, 0x100
	v_mov_b32_e32 v228, 0xff800000
	v_writelane_b32 v253, s5, 45
	s_cselect_b64 s[4:5], -1, 0
	v_writelane_b32 v253, s4, 46
	s_cmpk_lg_i32 s60, 0x100
	v_mov_b32_e32 v236, v191
	v_writelane_b32 v253, s5, 47
	s_cselect_b64 s[4:5], -1, 0
	v_writelane_b32 v253, s4, 48
	s_cmpk_lt_i32 s90, 0x100
	v_mov_b32_e32 v237, v191
	v_writelane_b32 v253, s5, 49
	s_cselect_b64 s[4:5], -1, 0
	v_writelane_b32 v253, s4, 50
	s_lshl_b32 s3, s10, 5
	v_mov_b64_e32 v[198:199], 0x100
	v_writelane_b32 v253, s5, 51
	s_getpc_b64 s[4:5]
	s_add_u32 s4, s4, g_ctl@rel32@lo+9220
	s_addc_u32 s5, s5, g_ctl@rel32@hi+9228
	s_getpc_b64 s[6:7]
	s_add_u32 s6, s6, g_ctl@rel32@lo+5124
	s_addc_u32 s7, s7, g_ctl@rel32@hi+5132
	s_cmp_lt_i32 s10, 0
	s_mul_i32 s10, s10, 33
	s_cselect_b32 s2, s12, s11
	s_cselect_b32 s3, s10, s3
	s_add_i32 s2, s2, s9
	v_lshl_add_u64 v[188:189], s[4:5], 0, v[0:1]
	s_ashr_i32 s4, s2, 31
	s_lshr_b32 s4, s4, 25
	s_add_i32 s4, s2, s4
	s_ashr_i32 s5, s4, 7
	s_and_b32 s4, s4, 0xff80
	s_sub_i32 s4, s2, s4
	s_bfe_i32 s2, s4, 0x80000
	s_bfe_u32 s2, s2, 0x3000c
	v_lshl_add_u64 v[186:187], s[6:7], 0, v[0:1]
	s_add_i32 s6, s4, s2
	s_bfe_i32 s2, s6, 0x80000
	s_and_b32 s6, s6, 0xf8
	s_sub_i32 s4, s4, s6
	s_lshl_b32 s5, s5, 3
	s_sext_i32_i16 s7, s2
	s_sext_i32_i8 s4, s4
	s_add_i32 s8, s5, s4
	s_ashr_i32 s4, s7, 3
	s_mov_b32 s100, 0x7654321b
	s_mov_b32 s101, 0xfedc9a08
	s_lshl_b32 s4, s4, 2
	s_lshr_b64 s[100:101], s[100:101], s4
	s_and_b32 s4, s100, 15
	s_add_i32 s3, s3, s9
	v_writelane_b32 v253, s4, 52
	s_ashr_i32 s4, s3, 31
	s_lshr_b32 s4, s4, 27
	s_add_i32 s4, s3, s4
	s_ashr_i32 s5, s4, 5
	s_and_b32 s4, s4, 0xffe0
	s_sub_i32 s3, s3, s4
	s_bfe_i32 s4, s3, 0x80000
	s_bfe_u32 s4, s4, 0x3000c
	s_add_i32 s6, s3, s4
	s_bfe_i32 s4, s6, 0x80000
	s_and_b32 s6, s6, 0xf8
	s_sub_i32 s3, s3, s6
	s_lshr_b32 s2, s7, 3
	s_mov_b32 s100, 0x7654321b
	s_mov_b32 s101, 0xfedc9a08
	s_lshl_b32 s2, s2, 2
	s_lshr_b64 s[100:101], s[100:101], s2
	s_and_b32 s2, s100, 15
	s_lshl_b32 s5, s5, 3
	s_sext_i32_i16 s7, s4
	s_sext_i32_i8 s3, s3
	s_add_i32 s10, s5, s3
	s_ashr_i32 s3, s7, 3
	v_writelane_b32 v253, s3, 53
	s_mov_b32 s6, s8
	s_lshr_b32 s4, s7, 3
	s_ashr_i32 s9, s8, 31
	v_writelane_b32 v253, s6, 54
	s_bfe_i64 s[2:3], s[2:3], 0x100000
	s_lshl_b64 s[2:3], s[2:3], 19
	v_writelane_b32 v253, s7, 55
	s_lshl_b64 s[6:7], s[8:9], 19
	v_writelane_b32 v253, s6, 56
	s_ashr_i32 s11, s10, 31
	s_ashr_i32 s79, s78, 31
	v_writelane_b32 v253, s7, 57
	v_writelane_b32 v253, s2, 58
	s_lshl_b32 s87, s60, 2
	v_mov_b64_e32 v[200:201], 0xff
	v_writelane_b32 v253, s3, 59
	s_mov_b32 s2, s10
	v_writelane_b32 v253, s2, 60
	s_mov_b32 s97, 0x18000
	s_mov_b32 s88, 0x1a000
	v_writelane_b32 v253, s3, 61
	s_lshl_b64 s[2:3], s[10:11], 19
	v_writelane_b32 v253, s2, 62
	s_mov_b32 s89, 0x8000
	s_mov_b32 s91, 0x1c000
	v_writelane_b32 v253, s3, 63
	s_bfe_i64 s[2:3], s[4:5], 0x100000
	s_lshl_b64 s[2:3], s[2:3], 19
	v_writelane_b32 v252, s2, 0
	s_mov_b32 s93, 0x800000
	s_mov_b32 s94, 0xbfb8aa3b
	v_writelane_b32 v252, s3, 1
	s_lshl_b32 s2, s78, 7
	v_writelane_b32 v252, s2, 2
	s_lshl_b32 s2, s60, 8
	v_writelane_b32 v252, s2, 3
	s_lshl_b32 s2, s78, 1
	v_writelane_b32 v252, s2, 4
	s_lshl_b64 s[2:3], s[78:79], 14
	s_add_u32 s2, s2, 0x1800000
	v_writelane_b32 v252, s2, 5
	s_addc_u32 s2, s3, 0
	s_ashr_i32 s73, s72, 31
	v_writelane_b32 v252, s2, 6
	s_lshl_b64 s[2:3], s[72:73], 14
	v_writelane_b32 v252, s2, 7
	s_mov_b32 s95, 0x3f317217
	s_mov_b32 s62, 0x7f800000
	v_writelane_b32 v252, s3, 8
	s_mov_b32 s2, s78
	v_writelane_b32 v252, s2, 9
	s_movk_i32 s70, 0x1e00
	s_movk_i32 s71, 0x90
	v_writelane_b32 v252, s3, 10
	s_lshl_b64 s[2:3], s[78:79], 8
	s_add_u32 s2, s2, 0x1600000
	v_writelane_b32 v252, s2, 11
	s_addc_u32 s2, s3, 0
	v_writelane_b32 v252, s2, 12
	s_add_i32 s2, 0, 0x23fc0
	v_writelane_b32 v252, s2, 13
	s_add_i32 s2, 0, 0x23fc4
	v_writelane_b32 v252, s2, 14
	s_add_i32 s2, 0, 0x4400
	v_writelane_b32 v252, s2, 15
	s_add_i32 s2, 0, 0x15c00
	v_writelane_b32 v252, s2, 16
	s_add_i32 s2, 0, 0x20800
	v_writelane_b32 v252, s2, 17
	s_lshl_b64 s[2:3], s[72:73], 8
	v_writelane_b32 v252, s2, 18
	s_movk_i32 s79, 0x4000
	s_mov_b32 s64, 0xb2a5705f
	s_mov_b32 s58, 0x42ce8ed0
	s_mov_b32 s59, 0xc2b17218
	s_mov_b32 s77, 0x3f2aaaab
	s_mov_b32 s78, 0x3f317218
	s_mov_b32 s63, 0x33800000
	s_movk_i32 s76, 0x1000
	s_mov_b32 s4, 0x9000
	s_mov_b32 s9, 0xb000
	s_mov_b32 s5, 0xf000
	s_mov_b32 s6, 0x11000
	s_mov_b32 s7, 0x13000
	s_mov_b32 s86, 0x15000
	s_mov_b32 s61, 0x17000
	v_writelane_b32 v252, s3, 19
	s_movk_i32 s73, 0x3000
	s_mov_b32 s67, 0xa000
	s_mov_b64 s[14:15], -1
	s_mov_b64 s[2:3], 0
	s_mov_b64 s[84:85], 0x80
	s_mov_b32 s8, 0x3c800000
	s_mov_b32 s16, s81
	s_barrier
	s_branch .LBB0_253

.LBB0_265:
	s_mov_b32 s2, 0x7654321b
	s_mov_b32 s3, 0xfedc9a08
	s_lshl_b32 s22, s22, 2
	s_lshr_b64 s[2:3], s[2:3], s22
	s_and_b32 s22, s2, 15
	s_ashr_i32 s25, s24, 31
	s_lshl_b64 s[26:27], s[24:25], 19
	s_add_u32 s26, s73, s26
	s_addc_u32 s27, s74, s27
	s_and_b64 s[28:29], s[40:41], exec
	s_cselect_b32 s25, s27, s31
	s_cselect_b32 s43, s26, s30
	s_ashr_i32 s23, s22, 31
	s_lshl_b64 s[28:29], s[22:23], 19
	s_add_u32 s28, s75, s28
	s_addc_u32 s29, s12, s29
	s_and_b64 s[36:37], s[40:41], exec
	s_cselect_b32 s23, s29, s35
	s_cselect_b32 s44, s28, s34
	s_add_u32 s30, s30, 0x40080
	s_addc_u32 s31, s31, 0
	s_add_u32 s45, s34, 0x100
	v_mov_b32_e32 v64, 0
	s_addc_u32 s46, s35, 0
	s_mov_b32 s47, -2
	v_mov_b32_e32 v65, v64
	v_mov_b32_e32 v66, v64
	v_mov_b32_e32 v67, v64
	v_mov_b32_e32 v68, v64
	v_mov_b32_e32 v69, v64
	v_mov_b32_e32 v70, v64
	v_mov_b32_e32 v71, v64
	v_mov_b32_e32 v72, v64
	v_mov_b32_e32 v73, v64
	v_mov_b32_e32 v74, v64
	v_mov_b32_e32 v75, v64
	v_mov_b32_e32 v76, v64
	v_mov_b32_e32 v77, v64
	v_mov_b32_e32 v78, v64
	v_mov_b32_e32 v79, v64
	v_mov_b32_e32 v80, v64
	v_mov_b32_e32 v81, v64
	v_mov_b32_e32 v82, v64
	v_mov_b32_e32 v83, v64
	v_mov_b32_e32 v84, v64
	v_mov_b32_e32 v85, v64
	v_mov_b32_e32 v86, v64
	v_mov_b32_e32 v87, v64
	v_mov_b32_e32 v88, v64
	v_mov_b32_e32 v89, v64
	v_mov_b32_e32 v90, v64
	v_mov_b32_e32 v91, v64
	v_mov_b32_e32 v92, v64
	v_mov_b32_e32 v93, v64
	v_mov_b32_e32 v94, v64
	v_mov_b32_e32 v95, v64
	v_mov_b32_e32 v0, v64
	v_mov_b32_e32 v1, v64
	v_mov_b32_e32 v2, v64
	v_mov_b32_e32 v3, v64
	v_mov_b32_e32 v4, v64
	v_mov_b32_e32 v5, v64
	v_mov_b32_e32 v6, v64
	v_mov_b32_e32 v7, v64
	v_mov_b32_e32 v8, v64
	v_mov_b32_e32 v9, v64
	v_mov_b32_e32 v10, v64
	v_mov_b32_e32 v11, v64
	v_mov_b32_e32 v12, v64
	v_mov_b32_e32 v13, v64
	v_mov_b32_e32 v14, v64
	v_mov_b32_e32 v15, v64
	v_mov_b32_e32 v16, v64
	v_mov_b32_e32 v17, v64
	v_mov_b32_e32 v18, v64
	v_mov_b32_e32 v19, v64
	v_mov_b32_e32 v20, v64
	v_mov_b32_e32 v21, v64
	v_mov_b32_e32 v22, v64
	v_mov_b32_e32 v23, v64
	v_mov_b32_e32 v24, v64
	v_mov_b32_e32 v25, v64
	v_mov_b32_e32 v26, v64
	v_mov_b32_e32 v27, v64
	v_mov_b32_e32 v28, v64
	v_mov_b32_e32 v29, v64
	v_mov_b32_e32 v30, v64
	v_mov_b32_e32 v31, v64
	v_mov_b32_e32 v96, v64
	v_mov_b32_e32 v97, v64
	v_mov_b32_e32 v98, v64
	v_mov_b32_e32 v99, v64
	v_mov_b32_e32 v100, v64
	v_mov_b32_e32 v101, v64
	v_mov_b32_e32 v102, v64
	v_mov_b32_e32 v103, v64
	v_mov_b32_e32 v104, v64
	v_mov_b32_e32 v105, v64
	v_mov_b32_e32 v106, v64
	v_mov_b32_e32 v107, v64
	v_mov_b32_e32 v108, v64
	v_mov_b32_e32 v109, v64
	v_mov_b32_e32 v110, v64
	v_mov_b32_e32 v111, v64
	v_mov_b32_e32 v112, v64
	v_mov_b32_e32 v113, v64
	v_mov_b32_e32 v114, v64
	v_mov_b32_e32 v115, v64
	v_mov_b32_e32 v116, v64
	v_mov_b32_e32 v117, v64
	v_mov_b32_e32 v118, v64
	v_mov_b32_e32 v119, v64
	v_mov_b32_e32 v120, v64
	v_mov_b32_e32 v121, v64
	v_mov_b32_e32 v122, v64
	v_mov_b32_e32 v123, v64
	v_mov_b32_e32 v124, v64
	v_mov_b32_e32 v125, v64
	v_mov_b32_e32 v126, v64
	v_mov_b32_e32 v127, v64
	v_mov_b32_e32 v32, v64
	v_mov_b32_e32 v33, v64
	v_mov_b32_e32 v34, v64
	v_mov_b32_e32 v35, v64
	v_mov_b32_e32 v36, v64
	v_mov_b32_e32 v37, v64
	v_mov_b32_e32 v38, v64
	v_mov_b32_e32 v39, v64
	v_mov_b32_e32 v40, v64
	v_mov_b32_e32 v41, v64
	v_mov_b32_e32 v42, v64
	v_mov_b32_e32 v43, v64
	v_mov_b32_e32 v44, v64
	v_mov_b32_e32 v45, v64
	v_mov_b32_e32 v46, v64
	v_mov_b32_e32 v47, v64
	v_mov_b32_e32 v48, v64
	v_mov_b32_e32 v49, v64
	v_mov_b32_e32 v50, v64
	v_mov_b32_e32 v51, v64
	v_mov_b32_e32 v52, v64
	v_mov_b32_e32 v53, v64
	v_mov_b32_e32 v54, v64
	v_mov_b32_e32 v55, v64
	v_mov_b32_e32 v56, v64
	v_mov_b32_e32 v57, v64
	v_mov_b32_e32 v58, v64
	v_mov_b32_e32 v59, v64
	v_mov_b32_e32 v60, v64
	v_mov_b32_e32 v61, v64
	v_mov_b32_e32 v62, v64
	v_mov_b32_e32 v63, v64
